# nt hint also on the mixer cache-copy loop's output stores (final outputs, never re-read)
# baseline (speedup 1.0000x reference)
; __device__ __forceinline__ int tid_() { int t = threadIdx.x; asm volatile("" : "+v"(t)); return t; }
; __device__ __forceinline__ float bf2f(u16 h) { return __uint_as_float(((unsigned)h) << 16); }
; __device__ void copy_item(const P& p, int item) {
;   int e = item * 2048 + tid_();
; #pragma unroll
;   for (int k = 0; k < 8; ++k, e += 256) {
;     int i = e;
;     if (i < 131072) {
;       int which = i >> 16; i &= 65535;
;       int d = i & 63, kvh = (i >> 6) & 1, wpos = (i >> 7) & 127, b = i >> 14;
;       float v = bf2f(p_proj[((size_t)b * 8192 + 8064 + wpos) * INW + 512 + which * 128 + kvh * 64 + d]);
;       p.out[(which ? O_VP : O_KP) + i] = v;
;     } else if ((i -= 131072) < 18432) {
;       int c = i % 1536, j = (i / 1536) % 3, b = i / 4608;
;       p.out[O_CP + i] = bf2f(p_proj[((size_t)b * 8192 + 8189 + j) * INW + 768 + c]);
;     } else if ((i -= 18432) < 4194304) {
;       int which = i >> 21; i &= 2097151;
;       int d = i & 63, kvh = (i >> 6) & 1, wpos = (i >> 7) & 127, b = i >> 14;
;       float v;
;       if (wpos < 120) v = (which ? p.cv : p.ck)[(((size_t)b * 128 + wpos + 8) * 2 + kvh) * 64 + d];
;       else v = bf2f(p_proj[((size_t)TP + b * 8 + wpos - 120) * INW + 512 + which * 128 + kvh * 64 + d]);
;       p.out[(which ? O_VS : O_KS) + i] = v;
;     } else {
;       i -= 4194304;
;       int c = i % 1536, j = (i / 1536) % 3, b = i / 4608;
;       p.out[O_CS + i] = bf2f(p_proj[((size_t)TP + b * 8 + 5 + j) * INW + 768 + c]);
;     }
;   }
; }
.LBB0_349:
	v_mov_b32_e32 v15, v220
	s_add_i32 s4, s14, s13
	s_nop 0
	v_add_u32_e32 v16, s4, v15
	v_add_u32_e32 v2, 0xffff0000, v16
	v_and_b32_e32 v4, 63, v15
	v_cmp_lt_i32_e32 vcc, s16, v2
	s_and_saveexec_b64 s[4:5], vcc
	s_xor_b64 s[4:5], exec, s[4:5]
	s_cbranch_execz .LBB0_363
	v_cmp_lt_u32_e32 vcc, s17, v2
	s_and_saveexec_b64 s[6:7], vcc
	s_xor_b64 s[6:7], exec, s[6:7]
	s_cbranch_execz .LBB0_360
	v_cmp_lt_u32_e32 vcc, s18, v2
	s_and_saveexec_b64 s[8:9], vcc
	s_xor_b64 s[8:9], exec, s[8:9]
	s_cbranch_execz .LBB0_353
	v_add_u32_e32 v3, 0xffbcb800, v16
	v_mul_hi_u32 v0, v3, s19
	v_lshrrev_b32_e32 v5, 10, v0
	v_mul_u32_u24_e32 v0, 0x600, v5
	v_mul_hi_u32 v6, v5, s20
	v_sub_u32_e32 v0, v3, v0
	v_mul_u32_u24_e32 v6, 3, v6
	v_mul_hi_u32 v3, v3, s21
	v_sub_u32_e32 v5, v5, v6
	v_lshrrev_b32_e32 v3, 7, v3
	v_and_or_b32 v3, v3, s22, v5
	v_add_u32_e32 v3, 0x8005, v3
	v_mov_b64_e32 v[6:7], s[0:1]
	v_mad_u64_u32 v[6:7], s[10:11], v3, s23, v[6:7]
	v_lshl_add_u64 v[6:7], v[0:1], 1, v[6:7]
	global_load_ushort v0, v[6:7], off
	v_readlane_b32 s44, v228, 2
	v_mov_b32_e32 v3, v1
	v_readlane_b32 s48, v228, 6
	v_readlane_b32 s49, v228, 7
	v_readlane_b32 s45, v228, 3
	v_readlane_b32 s46, v228, 4
	v_lshl_add_u64 v[6:7], v[2:3], 2, s[48:49]
	v_add_co_u32_e32 v6, vcc, 0x8480000, v6
	v_readlane_b32 s47, v228, 5
	s_nop 0
	v_addc_co_u32_e32 v7, vcc, 0, v7, vcc
	v_readlane_b32 s50, v228, 8
	v_readlane_b32 s51, v228, 9
	s_waitcnt vmcnt(0)
	v_lshlrev_b32_e32 v0, 16, v0
	global_store_dword v[6:7], v0, off nt

; __device__ __forceinline__ float bf2f(u16 h) { return __uint_as_float(((unsigned)h) << 16); }
; __device__ void copy_item(const P& p, int item) {
;     ...
;     } else if ((i -= 18432) < 4194304) {
;       int which = i >> 21; i &= 2097151;
;       int d = i & 63, kvh = (i >> 6) & 1, wpos = (i >> 7) & 127, b = i >> 14;
;       float v;
;       if (wpos < 120) v = (which ? p.cv : p.ck)[(((size_t)b * 128 + wpos + 8) * 2 + kvh) * 64 + d];
;       else v = bf2f(p_proj[((size_t)TP + b * 8 + wpos - 120) * INW + 512 + which * 128 + kvh * 64 + d]);
;       p.out[(which ? O_VS : O_KS) + i] = v;
.LBB0_358:
	s_or_b64 exec, exec, s[10:11]
	v_cmp_gt_u32_e32 vcc, s25, v3
	v_and_b32_e32 v0, 0x1fffff, v3
	v_readlane_b32 s44, v228, 2
	v_cndmask_b32_e32 v3, v10, v11, vcc
	v_add_lshl_u32 v0, v3, v0, 2
	v_readlane_b32 s48, v228, 6
	v_readlane_b32 s49, v228, 7
	v_readlane_b32 s45, v228, 3
	v_readlane_b32 s46, v228, 4
	v_readlane_b32 s47, v228, 5
	v_readlane_b32 s50, v228, 8
	v_readlane_b32 s51, v228, 9
	s_waitcnt vmcnt(0)
	global_store_dword v0, v5, s[48:49] nt

; __device__ __forceinline__ float bf2f(u16 h) { return __uint_as_float(((unsigned)h) << 16); }
; __device__ void copy_item(const P& p, int item) {
;     ...
;     } else if ((i -= 131072) < 18432) {
;       int c = i % 1536, j = (i / 1536) % 3, b = i / 4608;
;       p.out[O_CP + i] = bf2f(p_proj[((size_t)b * 8192 + 8189 + j) * INW + 768 + c]);
.LBB0_360:
	s_andn2_saveexec_b64 s[6:7], s[6:7]
	s_cbranch_execz .LBB0_362
	v_mul_u32_u24_sdwa v0, v2, s28 dst_sel:DWORD dst_unused:UNUSED_PAD src0_sel:WORD_0 src1_sel:DWORD
	v_lshrrev_b32_e32 v0, 26, v0
	v_mul_lo_u16_e32 v5, 0x56, v0
	v_mul_lo_u16_sdwa v5, v5, v12 dst_sel:DWORD dst_unused:UNUSED_PAD src0_sel:BYTE_1 src1_sel:DWORD
	v_mul_lo_u16_e32 v3, 0x600, v0
	v_sub_u16_e32 v0, v0, v5
	v_mul_u32_u24_sdwa v5, v2, s29 dst_sel:DWORD dst_unused:UNUSED_PAD src0_sel:WORD_0 src1_sel:DWORD
	v_lshrrev_b32_e32 v5, 15, v5
	v_and_b32_e32 v5, 0x1e000, v5
	v_and_or_b32 v0, v0, s30, v5
	v_add_u32_e32 v0, 0x1ffd, v0
	v_mov_b64_e32 v[6:7], s[0:1]
	v_mad_u64_u32 v[6:7], s[8:9], v0, s23, v[6:7]
	v_sub_u16_e32 v0, v2, v3
	v_lshlrev_b32_e32 v0, 1, v0
	v_lshl_add_u64 v[6:7], v[6:7], 0, v[0:1]
	global_load_ushort v0, v[6:7], off
	v_readlane_b32 s44, v228, 2
	v_mov_b32_e32 v3, v1
	v_readlane_b32 s48, v228, 6
	v_readlane_b32 s49, v228, 7
	v_readlane_b32 s45, v228, 3
	v_readlane_b32 s46, v228, 4
	v_lshl_add_u64 v[6:7], v[2:3], 2, s[48:49]
	v_add_co_u32_e32 v6, vcc, 0x8400000, v6
	v_readlane_b32 s47, v228, 5
	s_nop 0
	v_addc_co_u32_e32 v7, vcc, 0, v7, vcc
	v_readlane_b32 s50, v228, 8
	v_readlane_b32 s51, v228, 9
	s_waitcnt vmcnt(0)
	v_lshlrev_b32_e32 v0, 16, v0
	global_store_dword v[6:7], v0, off nt

; __device__ __forceinline__ int tid_() { int t = threadIdx.x; asm volatile("" : "+v"(t)); return t; }
; __device__ __forceinline__ float bf2f(u16 h) { return __uint_as_float(((unsigned)h) << 16); }
; __device__ void copy_item(const P& p, int item) {
;   int e = item * 2048 + tid_();
; #pragma unroll
;   for (int k = 0; k < 8; ++k, e += 256) {
;     int i = e;
;     if (i < 131072) {
;       int which = i >> 16; i &= 65535;
;       int d = i & 63, kvh = (i >> 6) & 1, wpos = (i >> 7) & 127, b = i >> 14;
;       float v = bf2f(p_proj[((size_t)b * 8192 + 8064 + wpos) * INW + 512 + which * 128 + kvh * 64 + d]);
;       p.out[(which ? O_VP : O_KP) + i] = v;
;     } else if ((i -= 131072) < 18432) {
;       int c = i % 1536, j = (i / 1536) % 3, b = i / 4608;
;       p.out[O_CP + i] = bf2f(p_proj[((size_t)b * 8192 + 8189 + j) * INW + 768 + c]);
.LBB0_363:
	s_or_saveexec_b64 s[4:5], s[4:5]
	v_and_b32_e32 v0, 64, v15
	v_lshlrev_b32_e32 v4, 1, v4
	v_lshlrev_b32_e32 v6, 1, v0
	s_xor_b64 exec, exec, s[4:5]
	s_cbranch_execz .LBB0_365
	v_bfe_u32 v0, v2, 7, 7
	v_lshrrev_b32_e32 v3, 1, v2
	v_readlane_b32 s44, v228, 2
	v_and_or_b32 v0, v3, s31, v0
	v_readlane_b32 s48, v228, 6
	v_readlane_b32 s49, v228, 7
	v_mul_u32_u24_e32 v0, 0xb10, v0
	v_ashrrev_i32_e32 v3, 9, v2
	v_readlane_b32 s50, v228, 8
	v_readlane_b32 s51, v228, 9
	s_mov_b64 s[8:9], s[48:49]
	v_and_b32_e32 v8, 0xffffff80, v3
	v_lshlrev_b32_e32 v0, 1, v0
	s_mov_b64 s[10:11], s[50:51]
	v_ashrrev_i32_e32 v9, 31, v8
	v_lshl_add_u64 v[18:19], s[10:11], 0, v[0:1]
	v_lshl_add_u64 v[8:9], v[8:9], 1, v[18:19]
	v_mov_b32_e32 v7, v1
	v_lshl_add_u64 v[8:9], v[8:9], 0, v[6:7]
	v_mov_b32_e32 v5, v1
	v_lshl_add_u64 v[8:9], v[8:9], 0, v[4:5]
	v_add_co_u32_e32 v8, vcc, 0xaccf000, v8
	v_readlane_b32 s45, v228, 3
	s_nop 0
	v_addc_co_u32_e32 v9, vcc, 0, v9, vcc
	global_load_ushort v0, v[8:9], off offset:1024
	v_cmp_gt_u32_e32 vcc, s34, v2
	v_readlane_b32 s46, v228, 4
	v_readlane_b32 s47, v228, 5
	v_cndmask_b32_e32 v3, v13, v14, vcc
	v_and_or_b32 v3, v2, s27, v3
	v_lshlrev_b32_e32 v3, 2, v3
	s_waitcnt vmcnt(0)
	v_lshlrev_b32_e32 v0, 16, v0
	global_store_dword v3, v0, s[8:9] nt
.LBB0_365:
	s_or_b64 exec, exec, s[4:5]
	v_add_u32_e32 v8, 0xffff0100, v16
	v_cmp_lt_i32_e32 vcc, s35, v2
	s_and_saveexec_b64 s[4:5], vcc
	s_xor_b64 s[4:5], exec, s[4:5]
	s_cbranch_execz .LBB0_379
	v_cmp_lt_u32_e32 vcc, s17, v8
	s_and_saveexec_b64 s[6:7], vcc
	s_xor_b64 s[6:7], exec, s[6:7]
	s_cbranch_execz .LBB0_376
	v_cmp_lt_u32_e32 vcc, s18, v8
	s_and_saveexec_b64 s[8:9], vcc
	s_xor_b64 s[8:9], exec, s[8:9]
	s_cbranch_execz .LBB0_369
	v_add_u32_e32 v3, 0xffbcb900, v16
	v_mul_hi_u32 v0, v3, s19
	v_lshrrev_b32_e32 v5, 10, v0
	v_mul_u32_u24_e32 v0, 0x600, v5
	v_mul_hi_u32 v7, v5, s20
	v_sub_u32_e32 v0, v3, v0
	v_mul_u32_u24_e32 v7, 3, v7
	v_mul_hi_u32 v3, v3, s21
	v_sub_u32_e32 v5, v5, v7
	v_lshrrev_b32_e32 v3, 7, v3
	v_and_or_b32 v3, v3, s22, v5
	v_add_u32_e32 v3, 0x8005, v3
	v_mov_b64_e32 v[18:19], s[0:1]
	v_mad_u64_u32 v[18:19], s[10:11], v3, s23, v[18:19]
	v_lshl_add_u64 v[18:19], v[0:1], 1, v[18:19]
	global_load_ushort v0, v[18:19], off
	v_readlane_b32 s44, v228, 2
	v_mov_b32_e32 v9, v1
	v_readlane_b32 s48, v228, 6
	v_readlane_b32 s49, v228, 7
	v_readlane_b32 s45, v228, 3
	v_readlane_b32 s46, v228, 4
	v_lshl_add_u64 v[8:9], v[8:9], 2, s[48:49]
	v_add_co_u32_e32 v8, vcc, 0x8480000, v8
	v_readlane_b32 s47, v228, 5
	s_nop 0
	v_addc_co_u32_e32 v9, vcc, 0, v9, vcc
	v_readlane_b32 s50, v228, 8
	v_readlane_b32 s51, v228, 9
	s_waitcnt vmcnt(0)
	v_lshlrev_b32_e32 v0, 16, v0
	global_store_dword v[8:9], v0, off nt

; __device__ __forceinline__ float bf2f(u16 h) { return __uint_as_float(((unsigned)h) << 16); }
; __device__ void copy_item(const P& p, int item) {
;     ...
;     } else if ((i -= 131072) < 18432) {
;       int c = i % 1536, j = (i / 1536) % 3, b = i / 4608;
;       p.out[O_CP + i] = bf2f(p_proj[((size_t)b * 8192 + 8189 + j) * INW + 768 + c]);
.LBB0_376:
	s_andn2_saveexec_b64 s[6:7], s[6:7]
	s_cbranch_execz .LBB0_378
	v_mul_u32_u24_sdwa v0, v8, s28 dst_sel:DWORD dst_unused:UNUSED_PAD src0_sel:WORD_0 src1_sel:DWORD
	v_lshrrev_b32_e32 v0, 26, v0
	v_mul_lo_u16_e32 v5, 0x56, v0
	v_mul_lo_u16_sdwa v5, v5, v12 dst_sel:DWORD dst_unused:UNUSED_PAD src0_sel:BYTE_1 src1_sel:DWORD
	v_mul_lo_u16_e32 v3, 0x600, v0
	v_sub_u16_e32 v0, v0, v5
	v_mul_u32_u24_sdwa v5, v8, s29 dst_sel:DWORD dst_unused:UNUSED_PAD src0_sel:WORD_0 src1_sel:DWORD
	v_lshrrev_b32_e32 v5, 15, v5
	v_and_b32_e32 v5, 0x1e000, v5
	v_and_or_b32 v0, v0, s30, v5
	v_add_u32_e32 v0, 0x1ffd, v0
	v_mov_b64_e32 v[18:19], s[0:1]
	v_mad_u64_u32 v[18:19], s[8:9], v0, s23, v[18:19]
	v_sub_u16_e32 v0, v8, v3
	v_lshlrev_b32_e32 v0, 1, v0
	v_lshl_add_u64 v[18:19], v[18:19], 0, v[0:1]
	global_load_ushort v0, v[18:19], off
	v_readlane_b32 s44, v228, 2
	v_mov_b32_e32 v9, v1
	v_readlane_b32 s48, v228, 6
	v_readlane_b32 s49, v228, 7
	v_readlane_b32 s45, v228, 3
	v_readlane_b32 s46, v228, 4
	v_lshl_add_u64 v[8:9], v[8:9], 2, s[48:49]
	v_add_co_u32_e32 v8, vcc, 0x8400000, v8
	v_readlane_b32 s47, v228, 5
	s_nop 0
	v_addc_co_u32_e32 v9, vcc, 0, v9, vcc
	v_readlane_b32 s50, v228, 8
	v_readlane_b32 s51, v228, 9
	s_waitcnt vmcnt(0)
	v_lshlrev_b32_e32 v0, 16, v0
	global_store_dword v[8:9], v0, off nt

; __device__ __forceinline__ int tid_() { int t = threadIdx.x; asm volatile("" : "+v"(t)); return t; }
; __device__ __forceinline__ float bf2f(u16 h) { return __uint_as_float(((unsigned)h) << 16); }
; __device__ void copy_item(const P& p, int item) {
;   int e = item * 2048 + tid_();
; #pragma unroll
;   for (int k = 0; k < 8; ++k, e += 256) {
;     int i = e;
;     if (i < 131072) {
;       int which = i >> 16; i &= 65535;
;       int d = i & 63, kvh = (i >> 6) & 1, wpos = (i >> 7) & 127, b = i >> 14;
;       float v = bf2f(p_proj[((size_t)b * 8192 + 8064 + wpos) * INW + 512 + which * 128 + kvh * 64 + d]);
;       p.out[(which ? O_VP : O_KP) + i] = v;
;     } else if ((i -= 131072) < 18432) {
;       int c = i % 1536, j = (i / 1536) % 3, b = i / 4608;
;       p.out[O_CP + i] = bf2f(p_proj[((size_t)b * 8192 + 8189 + j) * INW + 768 + c]);
;     } else if ((i -= 18432) < 4194304) {
;       int which = i >> 21; i &= 2097151;
;       int d = i & 63, kvh = (i >> 6) & 1, wpos = (i >> 7) & 127, b = i >> 14;
;       float v;
;       if (wpos < 120) v = (which ? p.cv : p.ck)[(((size_t)b * 128 + wpos + 8) * 2 + kvh) * 64 + d];
;       else v = bf2f(p_proj[((size_t)TP + b * 8 + wpos - 120) * INW + 512 + which * 128 + kvh * 64 + d]);
;       p.out[(which ? O_VS : O_KS) + i] = v;
;     } else {
;       i -= 4194304;
;       int c = i % 1536, j = (i / 1536) % 3, b = i / 4608;
;       p.out[O_CS + i] = bf2f(p_proj[((size_t)TP + b * 8 + 5 + j) * INW + 768 + c]);
;     }
;   }
; }
.LBB0_379:
	s_andn2_saveexec_b64 s[4:5], s[4:5]
	s_cbranch_execz .LBB0_381
	v_bfe_u32 v0, v8, 7, 7
	v_lshrrev_b32_e32 v3, 1, v8
	v_readlane_b32 s44, v228, 2
	v_and_or_b32 v0, v3, s31, v0
	v_readlane_b32 s48, v228, 6
	v_readlane_b32 s49, v228, 7
	v_mul_u32_u24_e32 v0, 0xb10, v0
	v_ashrrev_i32_e32 v3, 9, v8
	v_readlane_b32 s50, v228, 8
	v_readlane_b32 s51, v228, 9
	s_mov_b64 s[8:9], s[48:49]
	v_and_b32_e32 v18, 0xffffff80, v3
	v_lshlrev_b32_e32 v0, 1, v0
	s_mov_b64 s[10:11], s[50:51]
	v_ashrrev_i32_e32 v19, 31, v18
	v_lshl_add_u64 v[20:21], s[10:11], 0, v[0:1]
	v_lshl_add_u64 v[18:19], v[18:19], 1, v[20:21]
	v_mov_b32_e32 v7, v1
	v_lshl_add_u64 v[18:19], v[18:19], 0, v[6:7]
	v_mov_b32_e32 v5, v1
	v_lshl_add_u64 v[18:19], v[18:19], 0, v[4:5]
	v_add_co_u32_e32 v18, vcc, 0xaccf000, v18
	v_readlane_b32 s45, v228, 3
	s_nop 0
	v_addc_co_u32_e32 v19, vcc, 0, v19, vcc
	global_load_ushort v0, v[18:19], off offset:1024
	v_cmp_gt_u32_e32 vcc, s34, v8
	v_readlane_b32 s46, v228, 4
	v_readlane_b32 s47, v228, 5
	v_cndmask_b32_e32 v3, v13, v14, vcc
	v_and_or_b32 v3, v8, s27, v3
	v_lshlrev_b32_e32 v3, 2, v3
	s_waitcnt vmcnt(0)
	v_lshlrev_b32_e32 v0, 16, v0
	global_store_dword v3, v0, s[8:9] nt
.LBB0_381:
	s_or_b64 exec, exec, s[4:5]
	v_add_u32_e32 v8, 0xffff0200, v16
	v_cmp_lt_i32_e32 vcc, s36, v2
	s_and_saveexec_b64 s[4:5], vcc
	s_xor_b64 s[4:5], exec, s[4:5]
	s_cbranch_execz .LBB0_395
	v_cmp_lt_u32_e32 vcc, s17, v8
	s_and_saveexec_b64 s[6:7], vcc
	s_xor_b64 s[6:7], exec, s[6:7]
	s_cbranch_execz .LBB0_392
	v_cmp_lt_u32_e32 vcc, s18, v8
	s_and_saveexec_b64 s[8:9], vcc
	s_xor_b64 s[8:9], exec, s[8:9]
	s_cbranch_execz .LBB0_385
	v_add_u32_e32 v3, 0xffbcba00, v16
	v_mul_hi_u32 v0, v3, s19
	v_lshrrev_b32_e32 v5, 10, v0
	v_mul_u32_u24_e32 v0, 0x600, v5
	v_mul_hi_u32 v7, v5, s20
	v_sub_u32_e32 v0, v3, v0
	v_mul_u32_u24_e32 v7, 3, v7
	v_mul_hi_u32 v3, v3, s21
	v_sub_u32_e32 v5, v5, v7
	v_lshrrev_b32_e32 v3, 7, v3
	v_and_or_b32 v3, v3, s22, v5
	v_add_u32_e32 v3, 0x8005, v3
	v_mov_b64_e32 v[18:19], s[0:1]
	v_mad_u64_u32 v[18:19], s[10:11], v3, s23, v[18:19]
	v_lshl_add_u64 v[18:19], v[0:1], 1, v[18:19]
	global_load_ushort v0, v[18:19], off
	v_readlane_b32 s44, v228, 2
	v_mov_b32_e32 v9, v1
	v_readlane_b32 s48, v228, 6
	v_readlane_b32 s49, v228, 7
	v_readlane_b32 s45, v228, 3
	v_readlane_b32 s46, v228, 4
	v_lshl_add_u64 v[8:9], v[8:9], 2, s[48:49]
	v_add_co_u32_e32 v8, vcc, 0x8480000, v8
	v_readlane_b32 s47, v228, 5
	s_nop 0
	v_addc_co_u32_e32 v9, vcc, 0, v9, vcc
	v_readlane_b32 s50, v228, 8
	v_readlane_b32 s51, v228, 9
	s_waitcnt vmcnt(0)
	v_lshlrev_b32_e32 v0, 16, v0
	global_store_dword v[8:9], v0, off nt

; __device__ __forceinline__ float bf2f(u16 h) { return __uint_as_float(((unsigned)h) << 16); }
; __device__ void copy_item(const P& p, int item) {
;     ...
;       int c = i % 1536, j = (i / 1536) % 3, b = i / 4608;
;       p.out[O_CS + i] = bf2f(p_proj[((size_t)TP + b * 8 + 5 + j) * INW + 768 + c]);
.LBB0_397:
	s_or_b64 exec, exec, s[4:5]
	v_add_u32_e32 v8, 0xffff0300, v16
	v_cmp_lt_i32_e32 vcc, s37, v2
	s_and_saveexec_b64 s[4:5], vcc
	s_xor_b64 s[4:5], exec, s[4:5]
	s_cbranch_execz .LBB0_411
	v_cmp_lt_u32_e32 vcc, s17, v8
	s_and_saveexec_b64 s[6:7], vcc
	s_xor_b64 s[6:7], exec, s[6:7]
	s_cbranch_execz .LBB0_408
	v_cmp_lt_u32_e32 vcc, s18, v8
	s_and_saveexec_b64 s[8:9], vcc
	s_xor_b64 s[8:9], exec, s[8:9]
	s_cbranch_execz .LBB0_401
	v_add_u32_e32 v3, 0xffbcbb00, v16
	v_mul_hi_u32 v0, v3, s19
	v_lshrrev_b32_e32 v5, 10, v0
	v_mul_u32_u24_e32 v0, 0x600, v5
	v_mul_hi_u32 v7, v5, s20
	v_sub_u32_e32 v0, v3, v0
	v_mul_u32_u24_e32 v7, 3, v7
	v_mul_hi_u32 v3, v3, s21
	v_sub_u32_e32 v5, v5, v7
	v_lshrrev_b32_e32 v3, 7, v3
	v_and_or_b32 v3, v3, s22, v5
	v_add_u32_e32 v3, 0x8005, v3
	v_mov_b64_e32 v[18:19], s[0:1]
	v_mad_u64_u32 v[18:19], s[10:11], v3, s23, v[18:19]
	v_lshl_add_u64 v[18:19], v[0:1], 1, v[18:19]
	global_load_ushort v0, v[18:19], off
	v_readlane_b32 s44, v228, 2
	v_mov_b32_e32 v9, v1
	v_readlane_b32 s48, v228, 6
	v_readlane_b32 s49, v228, 7
	v_readlane_b32 s45, v228, 3
	v_readlane_b32 s46, v228, 4
	v_lshl_add_u64 v[8:9], v[8:9], 2, s[48:49]
	v_add_co_u32_e32 v8, vcc, 0x8480000, v8
	v_readlane_b32 s47, v228, 5
	s_nop 0
	v_addc_co_u32_e32 v9, vcc, 0, v9, vcc
	v_readlane_b32 s50, v228, 8
	v_readlane_b32 s51, v228, 9
	s_waitcnt vmcnt(0)
	v_lshlrev_b32_e32 v0, 16, v0
	global_store_dword v[8:9], v0, off nt

; __device__ __forceinline__ float bf2f(u16 h) { return __uint_as_float(((unsigned)h) << 16); }
; __device__ void copy_item(const P& p, int item) {
;     ...
;       int c = i % 1536, j = (i / 1536) % 3, b = i / 4608;
;       p.out[O_CS + i] = bf2f(p_proj[((size_t)TP + b * 8 + 5 + j) * INW + 768 + c]);
.LBB0_413:
	s_or_b64 exec, exec, s[4:5]
	v_add_u32_e32 v8, 0xffff0400, v16
	v_cmp_lt_i32_e32 vcc, s38, v2
	s_and_saveexec_b64 s[4:5], vcc
	s_xor_b64 s[4:5], exec, s[4:5]
	s_cbranch_execz .LBB0_427
	v_cmp_lt_u32_e32 vcc, s17, v8
	s_and_saveexec_b64 s[6:7], vcc
	s_xor_b64 s[6:7], exec, s[6:7]
	s_cbranch_execz .LBB0_424
	v_cmp_lt_u32_e32 vcc, s18, v8
	s_and_saveexec_b64 s[8:9], vcc
	s_xor_b64 s[8:9], exec, s[8:9]
	s_cbranch_execz .LBB0_417
	v_add_u32_e32 v3, 0xffbcbc00, v16
	v_mul_hi_u32 v0, v3, s19
	v_lshrrev_b32_e32 v5, 10, v0
	v_mul_u32_u24_e32 v0, 0x600, v5
	v_mul_hi_u32 v7, v5, s20
	v_sub_u32_e32 v0, v3, v0
	v_mul_u32_u24_e32 v7, 3, v7
	v_mul_hi_u32 v3, v3, s21
	v_sub_u32_e32 v5, v5, v7
	v_lshrrev_b32_e32 v3, 7, v3
	v_and_or_b32 v3, v3, s22, v5
	v_add_u32_e32 v3, 0x8005, v3
	v_mov_b64_e32 v[18:19], s[0:1]
	v_mad_u64_u32 v[18:19], s[10:11], v3, s23, v[18:19]
	v_lshl_add_u64 v[18:19], v[0:1], 1, v[18:19]
	global_load_ushort v0, v[18:19], off
	v_readlane_b32 s44, v228, 2
	v_mov_b32_e32 v9, v1
	v_readlane_b32 s48, v228, 6
	v_readlane_b32 s49, v228, 7
	v_readlane_b32 s45, v228, 3
	v_readlane_b32 s46, v228, 4
	v_lshl_add_u64 v[8:9], v[8:9], 2, s[48:49]
	v_add_co_u32_e32 v8, vcc, 0x8480000, v8
	v_readlane_b32 s47, v228, 5
	s_nop 0
	v_addc_co_u32_e32 v9, vcc, 0, v9, vcc
	v_readlane_b32 s50, v228, 8
	v_readlane_b32 s51, v228, 9
	s_waitcnt vmcnt(0)
	v_lshlrev_b32_e32 v0, 16, v0
	global_store_dword v[8:9], v0, off nt

; __device__ __forceinline__ float bf2f(u16 h) { return __uint_as_float(((unsigned)h) << 16); }
; __device__ void copy_item(const P& p, int item) {
;     ...
;       int c = i % 1536, j = (i / 1536) % 3, b = i / 4608;
;       p.out[O_CS + i] = bf2f(p_proj[((size_t)TP + b * 8 + 5 + j) * INW + 768 + c]);
.LBB0_429:
	s_or_b64 exec, exec, s[4:5]
	v_add_u32_e32 v8, 0xffff0500, v16
	v_cmp_lt_i32_e32 vcc, s39, v2
	s_and_saveexec_b64 s[4:5], vcc
	s_xor_b64 s[4:5], exec, s[4:5]
	s_cbranch_execz .LBB0_443
	v_cmp_lt_u32_e32 vcc, s17, v8
	s_and_saveexec_b64 s[6:7], vcc
	s_xor_b64 s[6:7], exec, s[6:7]
	s_cbranch_execz .LBB0_440
	v_cmp_lt_u32_e32 vcc, s18, v8
	s_and_saveexec_b64 s[8:9], vcc
	s_xor_b64 s[8:9], exec, s[8:9]
	s_cbranch_execz .LBB0_433
	v_add_u32_e32 v3, 0xffbcbd00, v16
	v_mul_hi_u32 v0, v3, s19
	v_lshrrev_b32_e32 v5, 10, v0
	v_mul_u32_u24_e32 v0, 0x600, v5
	v_mul_hi_u32 v7, v5, s20
	v_sub_u32_e32 v0, v3, v0
	v_mul_u32_u24_e32 v7, 3, v7
	v_mul_hi_u32 v3, v3, s21
	v_sub_u32_e32 v5, v5, v7
	v_lshrrev_b32_e32 v3, 7, v3
	v_and_or_b32 v3, v3, s22, v5
	v_add_u32_e32 v3, 0x8005, v3
	v_mov_b64_e32 v[18:19], s[0:1]
	v_mad_u64_u32 v[18:19], s[10:11], v3, s23, v[18:19]
	v_lshl_add_u64 v[18:19], v[0:1], 1, v[18:19]
	global_load_ushort v0, v[18:19], off
	v_readlane_b32 s44, v228, 2
	v_mov_b32_e32 v9, v1
	v_readlane_b32 s48, v228, 6
	v_readlane_b32 s49, v228, 7
	v_readlane_b32 s45, v228, 3
	v_readlane_b32 s46, v228, 4
	v_lshl_add_u64 v[8:9], v[8:9], 2, s[48:49]
	v_add_co_u32_e32 v8, vcc, 0x8480000, v8
	v_readlane_b32 s47, v228, 5
	s_nop 0
	v_addc_co_u32_e32 v9, vcc, 0, v9, vcc
	v_readlane_b32 s50, v228, 8
	v_readlane_b32 s51, v228, 9
	s_waitcnt vmcnt(0)
	v_lshlrev_b32_e32 v0, 16, v0
	global_store_dword v[8:9], v0, off nt

; __device__ __forceinline__ float bf2f(u16 h) { return __uint_as_float(((unsigned)h) << 16); }
; __device__ void copy_item(const P& p, int item) {
;     ...
;       int c = i % 1536, j = (i / 1536) % 3, b = i / 4608;
;       p.out[O_CS + i] = bf2f(p_proj[((size_t)TP + b * 8 + 5 + j) * INW + 768 + c]);
.LBB0_445:
	s_or_b64 exec, exec, s[4:5]
	v_add_u32_e32 v8, 0xffff0600, v16
	v_cmp_lt_i32_e32 vcc, s40, v2
	s_and_saveexec_b64 s[4:5], vcc
	s_xor_b64 s[4:5], exec, s[4:5]
	s_cbranch_execz .LBB0_459
	v_cmp_lt_u32_e32 vcc, s17, v8
	s_and_saveexec_b64 s[6:7], vcc
	s_xor_b64 s[6:7], exec, s[6:7]
	s_cbranch_execz .LBB0_456
	v_cmp_lt_u32_e32 vcc, s18, v8
	s_and_saveexec_b64 s[8:9], vcc
	s_xor_b64 s[8:9], exec, s[8:9]
	s_cbranch_execz .LBB0_449
	v_add_u32_e32 v3, 0xffbcbe00, v16
	v_mul_hi_u32 v0, v3, s19
	v_lshrrev_b32_e32 v5, 10, v0
	v_mul_u32_u24_e32 v0, 0x600, v5
	v_mul_hi_u32 v7, v5, s20
	v_sub_u32_e32 v0, v3, v0
	v_mul_u32_u24_e32 v7, 3, v7
	v_mul_hi_u32 v3, v3, s21
	v_sub_u32_e32 v5, v5, v7
	v_lshrrev_b32_e32 v3, 7, v3
	v_and_or_b32 v3, v3, s22, v5
	v_add_u32_e32 v3, 0x8005, v3
	v_mov_b64_e32 v[18:19], s[0:1]
	v_mad_u64_u32 v[18:19], s[10:11], v3, s23, v[18:19]
	v_lshl_add_u64 v[18:19], v[0:1], 1, v[18:19]
	global_load_ushort v0, v[18:19], off
	v_readlane_b32 s44, v228, 2
	v_mov_b32_e32 v9, v1
	v_readlane_b32 s48, v228, 6
	v_readlane_b32 s49, v228, 7
	v_readlane_b32 s45, v228, 3
	v_readlane_b32 s46, v228, 4
	v_lshl_add_u64 v[8:9], v[8:9], 2, s[48:49]
	v_add_co_u32_e32 v8, vcc, 0x8480000, v8
	v_readlane_b32 s47, v228, 5
	s_nop 0
	v_addc_co_u32_e32 v9, vcc, 0, v9, vcc
	v_readlane_b32 s50, v228, 8
	v_readlane_b32 s51, v228, 9
	s_waitcnt vmcnt(0)
	v_lshlrev_b32_e32 v0, 16, v0
	global_store_dword v[8:9], v0, off nt

; __device__ __forceinline__ float bf2f(u16 h) { return __uint_as_float(((unsigned)h) << 16); }
; __device__ void copy_item(const P& p, int item) {
;     ...
;       int c = i % 1536, j = (i / 1536) % 3, b = i / 4608;
;       p.out[O_CS + i] = bf2f(p_proj[((size_t)TP + b * 8 + 5 + j) * INW + 768 + c]);
.LBB0_461:
	s_or_b64 exec, exec, s[4:5]
	v_add_u32_e32 v8, 0xffff0700, v16
	v_cmp_lt_i32_e32 vcc, s41, v2
	s_and_saveexec_b64 s[4:5], vcc
	s_xor_b64 s[4:5], exec, s[4:5]
	s_cbranch_execz .LBB0_475
	v_cmp_lt_u32_e32 vcc, s17, v8
	s_and_saveexec_b64 s[6:7], vcc
	s_xor_b64 s[6:7], exec, s[6:7]
	s_cbranch_execz .LBB0_472
	v_cmp_lt_u32_e32 vcc, s18, v8
	s_and_saveexec_b64 s[8:9], vcc
	s_xor_b64 s[8:9], exec, s[8:9]
	s_cbranch_execz .LBB0_465
	v_add_u32_e32 v2, 0xffbcbf00, v16
	v_mul_hi_u32 v0, v2, s19
	v_lshrrev_b32_e32 v3, 10, v0
	v_mul_u32_u24_e32 v0, 0x600, v3
	v_mul_hi_u32 v4, v3, s20
	v_sub_u32_e32 v0, v2, v0
	v_mul_u32_u24_e32 v4, 3, v4
	v_mul_hi_u32 v2, v2, s21
	v_sub_u32_e32 v3, v3, v4
	v_lshrrev_b32_e32 v2, 7, v2
	v_and_or_b32 v2, v2, s22, v3
	v_add_u32_e32 v4, 0x8005, v2
	v_mov_b64_e32 v[2:3], s[0:1]
	v_mad_u64_u32 v[2:3], s[10:11], v4, s23, v[2:3]
	v_lshl_add_u64 v[2:3], v[0:1], 1, v[2:3]
	global_load_ushort v0, v[2:3], off
	v_readlane_b32 s44, v228, 2
	v_mov_b32_e32 v9, v1
	v_readlane_b32 s48, v228, 6
	v_readlane_b32 s49, v228, 7
	v_readlane_b32 s45, v228, 3
	v_readlane_b32 s46, v228, 4
	v_lshl_add_u64 v[2:3], v[8:9], 2, s[48:49]
	v_add_co_u32_e32 v2, vcc, 0x8480000, v2
	v_readlane_b32 s47, v228, 5
	s_nop 0
	v_addc_co_u32_e32 v3, vcc, 0, v3, vcc
	v_readlane_b32 s50, v228, 8
	v_readlane_b32 s51, v228, 9
	s_waitcnt vmcnt(0)
	v_lshlrev_b32_e32 v0, 16, v0
	global_store_dword v[2:3], v0, off nt

; __device__ __forceinline__ float bf2f(u16 h) { return __uint_as_float(((unsigned)h) << 16); }
; __device__ void copy_item(const P& p, int item) {
;     ...
;     } else if ((i -= 18432) < 4194304) {
;       int which = i >> 21; i &= 2097151;
;       int d = i & 63, kvh = (i >> 6) & 1, wpos = (i >> 7) & 127, b = i >> 14;
;       float v;
;       if (wpos < 120) v = (which ? p.cv : p.ck)[(((size_t)b * 128 + wpos + 8) * 2 + kvh) * 64 + d];
;       else v = bf2f(p_proj[((size_t)TP + b * 8 + wpos - 120) * INW + 512 + which * 128 + kvh * 64 + d]);
;       p.out[(which ? O_VS : O_KS) + i] = v;
.LBB0_470:
	s_or_b64 exec, exec, s[10:11]
	v_cmp_gt_u32_e32 vcc, s25, v2
	v_and_b32_e32 v0, 0x1fffff, v2
	v_readlane_b32 s44, v228, 2
	v_cndmask_b32_e32 v2, v10, v11, vcc
	v_add_lshl_u32 v0, v2, v0, 2
	v_readlane_b32 s48, v228, 6
	v_readlane_b32 s49, v228, 7
	v_readlane_b32 s45, v228, 3
	v_readlane_b32 s46, v228, 4
	v_readlane_b32 s47, v228, 5
	v_readlane_b32 s50, v228, 8
	v_readlane_b32 s51, v228, 9
	s_waitcnt vmcnt(0)
	global_store_dword v0, v3, s[48:49] nt

; __device__ __forceinline__ float bf2f(u16 h) { return __uint_as_float(((unsigned)h) << 16); }
; __device__ void copy_item(const P& p, int item) {
;     ...
;     } else if ((i -= 131072) < 18432) {
;       int c = i % 1536, j = (i / 1536) % 3, b = i / 4608;
;       p.out[O_CP + i] = bf2f(p_proj[((size_t)b * 8192 + 8189 + j) * INW + 768 + c]);
.LBB0_472:
	s_andn2_saveexec_b64 s[6:7], s[6:7]
	s_cbranch_execz .LBB0_474
	v_mul_u32_u24_sdwa v0, v8, s28 dst_sel:DWORD dst_unused:UNUSED_PAD src0_sel:WORD_0 src1_sel:DWORD
	v_lshrrev_b32_e32 v0, 26, v0
	v_mul_lo_u16_e32 v2, 0x56, v0
	v_mul_lo_u16_sdwa v2, v2, v12 dst_sel:DWORD dst_unused:UNUSED_PAD src0_sel:BYTE_1 src1_sel:DWORD
	v_mul_lo_u16_e32 v4, 0x600, v0
	v_sub_u16_e32 v0, v0, v2
	v_mul_u32_u24_sdwa v2, v8, s29 dst_sel:DWORD dst_unused:UNUSED_PAD src0_sel:WORD_0 src1_sel:DWORD
	v_lshrrev_b32_e32 v2, 15, v2
	v_and_b32_e32 v2, 0x1e000, v2
	v_and_or_b32 v0, v0, s30, v2
	v_add_u32_e32 v0, 0x1ffd, v0
	v_mov_b64_e32 v[2:3], s[0:1]
	v_mad_u64_u32 v[2:3], s[8:9], v0, s23, v[2:3]
	v_sub_u16_e32 v0, v8, v4
	v_lshlrev_b32_e32 v0, 1, v0
	v_lshl_add_u64 v[2:3], v[2:3], 0, v[0:1]
	global_load_ushort v0, v[2:3], off
	v_readlane_b32 s44, v228, 2
	v_mov_b32_e32 v9, v1
	v_readlane_b32 s48, v228, 6
	v_readlane_b32 s49, v228, 7
	v_readlane_b32 s45, v228, 3
	v_readlane_b32 s46, v228, 4
	v_lshl_add_u64 v[2:3], v[8:9], 2, s[48:49]
	v_add_co_u32_e32 v2, vcc, 0x8400000, v2
	v_readlane_b32 s47, v228, 5
	s_nop 0
	v_addc_co_u32_e32 v3, vcc, 0, v3, vcc
	v_readlane_b32 s50, v228, 8
	v_readlane_b32 s51, v228, 9
	s_waitcnt vmcnt(0)
	v_lshlrev_b32_e32 v0, 16, v0
	global_store_dword v[2:3], v0, off nt

; __device__ __forceinline__ int tid_() { int t = threadIdx.x; asm volatile("" : "+v"(t)); return t; }
; __device__ __forceinline__ float bf2f(u16 h) { return __uint_as_float(((unsigned)h) << 16); }
; __device__ void copy_item(const P& p, int item) {
;   int e = item * 2048 + tid_();
; #pragma unroll
;   for (int k = 0; k < 8; ++k, e += 256) {
;     int i = e;
;     if (i < 131072) {
;       int which = i >> 16; i &= 65535;
;       int d = i & 63, kvh = (i >> 6) & 1, wpos = (i >> 7) & 127, b = i >> 14;
;       float v = bf2f(p_proj[((size_t)b * 8192 + 8064 + wpos) * INW + 512 + which * 128 + kvh * 64 + d]);
;       p.out[(which ? O_VP : O_KP) + i] = v;
;     } else if ((i -= 131072) < 18432) {
;       int c = i % 1536, j = (i / 1536) % 3, b = i / 4608;
;       p.out[O_CP + i] = bf2f(p_proj[((size_t)b * 8192 + 8189 + j) * INW + 768 + c]);
.LBB0_475:
	s_andn2_saveexec_b64 s[4:5], s[4:5]
	s_cbranch_execz .LBB0_348
	v_bfe_u32 v0, v8, 7, 7
	v_lshrrev_b32_e32 v2, 1, v8
	v_readlane_b32 s44, v228, 2
	v_and_or_b32 v0, v2, s31, v0
	v_readlane_b32 s48, v228, 6
	v_readlane_b32 s49, v228, 7
	v_mul_u32_u24_e32 v0, 0xb10, v0
	v_ashrrev_i32_e32 v2, 9, v8
	v_readlane_b32 s50, v228, 8
	v_readlane_b32 s51, v228, 9
	s_mov_b64 s[8:9], s[48:49]
	v_and_b32_e32 v2, 0xffffff80, v2
	v_lshlrev_b32_e32 v0, 1, v0
	s_mov_b64 s[10:11], s[50:51]
	v_ashrrev_i32_e32 v3, 31, v2
	v_lshl_add_u64 v[16:17], s[10:11], 0, v[0:1]
	v_lshl_add_u64 v[2:3], v[2:3], 1, v[16:17]
	v_mov_b32_e32 v7, v1
	v_lshl_add_u64 v[2:3], v[2:3], 0, v[6:7]
	v_mov_b32_e32 v5, v1
	v_lshl_add_u64 v[2:3], v[2:3], 0, v[4:5]
	v_add_co_u32_e32 v2, vcc, 0xaccf000, v2
	v_readlane_b32 s45, v228, 3
	s_nop 0
	v_addc_co_u32_e32 v3, vcc, 0, v3, vcc
	global_load_ushort v0, v[2:3], off offset:1024
	v_cmp_gt_u32_e32 vcc, s34, v8
	v_readlane_b32 s46, v228, 4
	v_readlane_b32 s47, v228, 5
	v_cndmask_b32_e32 v2, v13, v14, vcc
	v_and_or_b32 v2, v8, s27, v2
	v_lshlrev_b32_e32 v2, 2, v2
	s_waitcnt vmcnt(0)
	v_lshlrev_b32_e32 v0, 16, v0
	global_store_dword v2, v0, s[8:9] nt
	s_branch .LBB0_348
